# v31: v28 + no L2 writeback by the XCD leader at the grid barrier (every store before it is write-through and drained per wave)
# baseline (speedup 1.0000x reference)
.LBB0_172:
	s_andn2_saveexec_b64 s[8:9], s[8:9]
	s_cbranch_execz .LBB0_192
	s_mov_b64 s[8:9], exec
	s_waitcnt lgkmcnt(0)
	s_waitcnt vmcnt(0)
	v_mbcnt_lo_u32_b32 v3, s8, 0
	v_mbcnt_hi_u32_b32 v3, s9, v3
	v_cmp_eq_u32_e32 vcc, 0, v3
	s_and_saveexec_b64 s[12:13], vcc
	s_cbranch_execz .LBB0_175
	s_bcnt1_i32_b64 s8, s[8:9]
	v_mov_b32_e32 v4, 0x4000
	v_mov_b32_e32 v5, s8
	global_atomic_add v4, v4, v5, s[24:25] offset:1024 sc0
